# phase 2: write-through (sc1) on the segment end-state stores that other XCDs read in the scan phase
# speedup vs baseline: 1.0053x; 1.0053x over previous
.LBB0_304:
	v_ashrrev_i32_e32 v65, 31, v64
	v_lshlrev_b32_e32 v66, 2, v72
	v_mov_b32_e32 v67, 0
	v_lshl_add_u64 v[66:67], s[0:1], 0, v[66:67]
	v_lshlrev_b64 v[64:65], 14, v[64:65]
	s_lshl_b64 s[6:7], s[4:5], 16
	v_lshl_add_u64 v[64:65], v[66:67], 0, v[64:65]
	v_lshl_add_u64 v[64:65], v[64:65], 0, s[6:7]
	v_add_co_u32_e32 v68, vcc, 0x1a900000, v64
	s_mov_b64 s[6:7], 0x1a900000
	s_nop 0
	v_addc_co_u32_e32 v69, vcc, 0, v65, vcc
	s_mov_b32 s5, 0x1a901000
	v_lshl_add_u64 v[66:67], v[64:65], 0, s[6:7]
	global_store_dword v[68:69], v0, off sc1
	global_store_dword v[66:67], v1, off offset:256 sc1
	global_store_dword v[66:67], v2, off offset:512 sc1
	global_store_dword v[66:67], v3, off offset:768 sc1
	global_store_dword v[66:67], v4, off offset:1024 sc1
	global_store_dword v[66:67], v5, off offset:1280 sc1
	global_store_dword v[66:67], v6, off offset:1536 sc1
	global_store_dword v[66:67], v7, off offset:1792 sc1
	global_store_dword v[66:67], v8, off offset:2048 sc1
	global_store_dword v[66:67], v9, off offset:2304 sc1
	global_store_dword v[66:67], v10, off offset:2560 sc1
	global_store_dword v[66:67], v11, off offset:2816 sc1
	global_store_dword v[66:67], v12, off offset:3072 sc1
	global_store_dword v[66:67], v13, off offset:3328 sc1
	global_store_dword v[66:67], v14, off offset:3584 sc1
	global_store_dword v[66:67], v15, off offset:3840 sc1
	v_add_co_u32_e32 v0, vcc, s5, v64
	s_mov_b32 s5, 0x1a902000
	s_nop 0
	v_addc_co_u32_e32 v1, vcc, 0, v65, vcc
	v_add_co_u32_e32 v2, vcc, s5, v64
	s_mov_b32 s5, 0x1a903000
	s_nop 0
	v_addc_co_u32_e32 v3, vcc, 0, v65, vcc
	global_store_dword v[2:3], v48, off offset:-4096 sc1
	global_store_dword v[0:1], v49, off offset:256 sc1
	global_store_dword v[0:1], v50, off offset:512 sc1
	global_store_dword v[0:1], v51, off offset:768 sc1
	global_store_dword v[0:1], v52, off offset:1024 sc1
	global_store_dword v[0:1], v53, off offset:1280 sc1
	global_store_dword v[0:1], v54, off offset:1536 sc1
	global_store_dword v[0:1], v55, off offset:1792 sc1
	global_store_dword v[0:1], v56, off offset:2048 sc1
	global_store_dword v[0:1], v57, off offset:2304 sc1
	global_store_dword v[0:1], v58, off offset:2560 sc1
	global_store_dword v[0:1], v59, off offset:2816 sc1
	global_store_dword v[0:1], v60, off offset:3072 sc1
	global_store_dword v[0:1], v61, off offset:3328 sc1
	global_store_dword v[0:1], v62, off offset:3584 sc1
	global_store_dword v[0:1], v63, off offset:3840 sc1
	global_store_dword v[2:3], v32, off sc1
	global_store_dword v[2:3], v33, off offset:256 sc1
	global_store_dword v[2:3], v34, off offset:512 sc1
	global_store_dword v[2:3], v35, off offset:768 sc1
	global_store_dword v[2:3], v36, off offset:1024 sc1
	global_store_dword v[2:3], v37, off offset:1280 sc1
	global_store_dword v[2:3], v38, off offset:1536 sc1
	global_store_dword v[2:3], v39, off offset:1792 sc1
	global_store_dword v[2:3], v40, off offset:2048 sc1
	global_store_dword v[2:3], v41, off offset:2304 sc1
	global_store_dword v[2:3], v42, off offset:2560 sc1
	global_store_dword v[2:3], v43, off offset:2816 sc1
	global_store_dword v[2:3], v44, off offset:3072 sc1
	global_store_dword v[2:3], v45, off offset:3328 sc1
	global_store_dword v[2:3], v46, off offset:3584 sc1
	global_store_dword v[2:3], v47, off offset:3840 sc1
	v_add_co_u32_e32 v0, vcc, s5, v64
	s_nop 1
	v_addc_co_u32_e32 v1, vcc, 0, v65, vcc
	global_store_dword v[0:1], v16, off sc1
	global_store_dword v[0:1], v17, off offset:256 sc1
	global_store_dword v[0:1], v18, off offset:512 sc1
	global_store_dword v[0:1], v19, off offset:768 sc1
	global_store_dword v[0:1], v20, off offset:1024 sc1
	global_store_dword v[0:1], v21, off offset:1280 sc1
	global_store_dword v[0:1], v22, off offset:1536 sc1
	global_store_dword v[0:1], v23, off offset:1792 sc1
	global_store_dword v[0:1], v24, off offset:2048 sc1
	global_store_dword v[0:1], v25, off offset:2304 sc1
	global_store_dword v[0:1], v26, off offset:2560 sc1
	global_store_dword v[0:1], v27, off offset:2816 sc1
	global_store_dword v[0:1], v28, off offset:3072 sc1
	global_store_dword v[0:1], v29, off offset:3328 sc1
	global_store_dword v[0:1], v30, off offset:3584 sc1
	global_store_dword v[0:1], v31, off offset:3840 sc1
	s_and_saveexec_b64 s[6:7], s[2:3]
	s_cbranch_execz .LBB0_306
	v_lshl_or_b32 v0, s4, 7, v71
	v_ashrrev_i32_e32 v1, 31, v0
	v_lshl_add_u64 v[0:1], v[0:1], 2, s[0:1]
	v_add_co_u32_e32 v0, vcc, 0x1c900000, v0
	s_nop 1
	v_addc_co_u32_e32 v1, vcc, 0, v1, vcc
	global_store_dword v[0:1], v70, off sc1
